# first attention item rows touched at the start of the state item (ranks<24) so they hit L2
# baseline (speedup 1.0000x reference)
; __device__ __forceinline__ void mlstm_state_group(const Args& a, LAS unsigned char* lds, int bh, int grp, int tid, int wave, int lane) {
;     const int b = bh >> 2, h = bh & 3;
;     const bf16_t* P = (const bf16_t*)(a.ws + WS_ACT);
;     const float* GT = (const float*)(a.ws + WS_GATES);
;     float* CG = (float*)(a.ws + WS_CG); float* NGs = (float*)(a.ws + WS_NG); float* SG = (float*)(a.ws + WS_SG); float* CHS = (float*)(a.ws + WS_CHS);
;     LAS bf16_t* VT = (LAS bf16_t*)(lds + ML2_VT); LAS bf16_t* KWT = (LAS bf16_t*)(lds + ML2_KWT);
;     LAS float* T_av = (LAS float*)(lds + ML_TB); LAS float* T_sc = T_av + 2048;
;     const int fr = lane & 15, fq = lane >> 4;
;     const float b_i = a.bi[h], b_f = a.bf[h];
;     const int c0 = grp * ML_GROUP;
;     const size_t rowbase = (size_t)b * SEQ;
;     const int lp = tid & 31, pcg = tid >> 5;
;     u32x4 rv[ML_GROUP][2]; u32x2 rk2[ML_GROUP][2];
; #pragma unroll
;     for (int ci = 0; ci < ML_GROUP; ++ci) { const size_t r0 = rowbase + (size_t)(c0 + ci) * 64;
; #pragma unroll
;         for (int i = 0; i < 2; ++i) { rv[ci][i] = *(const u32x4*)(P + (r0 + 2 * lp + i) * NIN + PC_VM + h * 128 + pcg * 8); rk2[ci][i] = *(const u32x2*)(P + (r0 + 2 * lp + i) * NIN + PC_KM + h * 64 + pcg * 4); } }
;     {
;         const size_t r = rowbase + (size_t)(c0 + wave) * 64 + lane;
;         const float gi = GT[r * 8 + h], gf = GT[r * 8 + 4 + h];
;         const float ipre = 15.f * fast_tanh((gi + b_i) * (1.f / 15.f)), fpre = 15.f * fast_tanh((gf + b_f) * (1.f / 15.f));
;         float bc = -__logf(1.f + __expf(-fpre));
; __device__ __forceinline__ void attn_item(const Args& a, LAS unsigned char* lds, int item, int tid, int wave, int lane) {
;     ...
;         const int kc = (t >> 2) < 192 ? (t >> 2) : 191, kpos = q0 - 128 + kc, kposc = kpos < 0 ? 0 : kpos;
;         const bf16_t* kp = P + (rowbase + kposc) * NIN + PC_KA + kvh * 64 + grp * 16; kk[it][0] = *(const u32x4*)kp; kk[it][1] = *(const u32x4*)(kp + 8);
;         const bf16_t* vp = P + (rowbase + kposc) * NIN + PC_VA + kvh * 64 + grp * 16; vv[it][0] = *(const u32x4*)vp; vv[it][1] = *(const u32x4*)(vp + 8);
;         const float* tkp = rope + (rowbase + kposc) * 16;
; #pragma unroll
;         for (int q = 0; q < 4; ++q) tk[it][q] = *(const f32x4*)(tkp + 4 * q);
;         const int qi = (t >> 2) & 63, gq = t >> 8;
;         const size_t row = rowbase + q0 + qi;
.LBB0_1078:
.LBB0_1079:
	s_mov_b32 s32, s81
	s_bfe_u32 s53, s32, 0x10005
	s_lshr_b32 s54, s32, 6
	s_lshl_b32 s55, s92, 1
	s_add_i32 s54, s54, s55
	s_lshl_b32 s54, s54, 11
	s_lshl_b32 s55, s81, 6
	s_add_i32 s70, s54, s55
	s_add_i32 s71, s55, 0xffffff80
	s_lshl_b32 s79, s53, 7
	s_add_i32 s79, s79, 0x1000
	s_lshl_b32 s80, s53, 9
	s_add_i32 s80, s80, 0xc00
	s_movk_i32 s82, 0x2400
	s_movk_i32 s83, 0xc0
	v_add_u32_e32 v148, s71, v153
	v_max_i32_e32 v148, 0, v148
	v_add_u32_e32 v148, s54, v148
	v_mul_lo_u32 v148, v148, s82
	v_add_u32_e32 v148, s79, v148
	v_subrev_u32_e32 v149, s83, v153
	v_min_u32_e32 v149, 0xff, v149
	v_lshrrev_b32_e32 v150, 2, v149
	v_and_b32_e32 v149, 3, v149
	v_add_u32_e32 v150, s70, v150
	v_mul_lo_u32 v150, v150, s82
	v_lshl_add_u32 v150, v149, 7, v150
	v_add_u32_e32 v150, s80, v150
	v_cmp_gt_u32_e64 s[66:67], s83, v153
	s_nop 1
	v_cndmask_b32_e64 v148, v150, v148, s[66:67]
	global_load_dword v151, v148, s[68:69]
	global_load_dword v151, v148, s[68:69] offset:256
	s_mul_hi_i32 s0, s81, 0x2aaaaaab
	s_lshr_b32 s1, s0, 31
	s_ashr_i32 s0, s0, 1
	s_add_i32 s0, s0, s1
	s_mul_i32 s1, s0, 12
	s_sub_i32 s1, s81, s1
	s_lshl_b32 s4, s92, 3
	s_lshl_b32 s0, s0, 2
	s_add_i32 s0, s0, s4
	s_mul_i32 s4, s1, 0x56
	s_bfe_u32 s5, s4, 0x1000f
	s_bfe_u32 s4, s4, 0x80008
	s_add_i32 s4, s4, s5
	s_sext_i32_i8 s5, s4
	s_mul_i32 s4, s4, 3
	s_add_i32 s0, s0, s5
	s_sub_i32 s1, s1, s4
	s_sext_i32_i8 s1, s1
	s_ashr_i32 s6, s0, 2
	s_lshl_b32 s10, s1, 3
	s_ashr_i32 s7, s6, 31
	s_lshl_b64 s[12:13], s[6:7], 11
	v_and_b32_e32 v109, 31, v153
	s_ashr_i32 s11, s10, 31
	v_lshl_or_b32 v4, v109, 1, s12
	v_mov_b32_e32 v5, s13
	s_lshl_b64 s[8:9], s[10:11], 6
	v_lshl_add_u64 v[6:7], v[4:5], 0, s[8:9]
	s_movk_i32 s25, 0x2400
	v_mov_b64_e32 v[2:3], s[68:69]
	s_and_b32 s14, s5, 3
	s_mov_b32 s5, 0
	v_mad_u64_u32 v[8:9], s[8:9], v6, s25, v[2:3]
	s_lshl_b32 s4, s14, 2
	v_lshrrev_b32_e32 v108, 5, v153
	v_mov_b32_e32 v1, 0
	v_mad_i32_i24 v9, v7, s25, v9
	s_lshl_b32 s8, s14, 8
	s_mov_b32 s9, s5
	v_mov_b32_e32 v0, s4
	s_lshl_b32 s6, s14, 7
	s_mov_b32 s7, s5
	s_waitcnt lgkmcnt(0)
	v_lshl_add_u64 v[10:11], v[8:9], 0, s[8:9]
	v_lshlrev_b32_e32 v6, 4, v108
	v_mov_b32_e32 v7, v1
	global_load_dword v28, v0, s[56:57]
	global_load_dword v16, v0, s[58:59]
	v_lshlrev_b32_e32 v0, 3, v108
	v_lshl_add_u64 v[10:11], v[10:11], 0, v[6:7]
	v_lshl_add_u64 v[8:9], v[8:9], 0, s[6:7]
	s_movk_i32 s24, 0x2000
	v_lshl_add_u64 v[8:9], v[8:9], 0, v[0:1]
	global_load_dwordx4 v[48:51], v[10:11], off offset:1024
	global_load_dwordx2 v[94:95], v[8:9], off offset:512
	v_add_co_u32_e32 v10, vcc, s24, v10
	s_or_b32 s14, s10, 1
	s_nop 0
	v_addc_co_u32_e32 v11, vcc, 0, v11, vcc
	v_add_co_u32_e32 v8, vcc, s24, v8
	s_ashr_i32 s15, s14, 31
	s_nop 0
	v_addc_co_u32_e32 v9, vcc, 0, v9, vcc
	s_lshl_b64 s[14:15], s[14:15], 6
	global_load_dwordx4 v[52:55], v[10:11], off offset:2048
	global_load_dwordx2 v[96:97], v[8:9], off offset:1536
	v_lshl_add_u64 v[8:9], v[4:5], 0, s[14:15]
	v_mad_u64_u32 v[10:11], s[14:15], v8, s25, v[2:3]
	v_mad_i32_i24 v11, v9, s25, v11
	v_lshl_add_u64 v[8:9], v[10:11], 0, s[8:9]
	v_lshl_add_u64 v[8:9], v[8:9], 0, v[6:7]
	v_lshl_add_u64 v[10:11], v[10:11], 0, s[6:7]
	v_lshl_add_u64 v[10:11], v[10:11], 0, v[0:1]
	global_load_dwordx4 v[40:43], v[8:9], off offset:1024
	global_load_dwordx2 v[90:91], v[10:11], off offset:512
	v_add_co_u32_e32 v8, vcc, s24, v8
	s_or_b32 s14, s10, 2
	s_nop 0
	v_addc_co_u32_e32 v9, vcc, 0, v9, vcc
	s_ashr_i32 s15, s14, 31
	s_or_b32 s18, s10, 5
	v_add_co_u32_e32 v10, vcc, s24, v10
	s_lshl_b64 s[14:15], s[14:15], 6
	s_ashr_i32 s19, s18, 31
	v_addc_co_u32_e32 v11, vcc, 0, v11, vcc
	global_load_dwordx4 v[44:47], v[8:9], off offset:2048
	global_load_dwordx2 v[92:93], v[10:11], off offset:1536
	v_lshl_add_u64 v[8:9], v[4:5], 0, s[14:15]
	s_lshl_b64 s[20:21], s[18:19], 6
	s_or_b32 s18, s10, 6
	v_mad_u64_u32 v[10:11], s[14:15], v8, s25, v[2:3]
	s_ashr_i32 s19, s18, 31
	s_or_b32 s14, s10, 3
	s_or_b32 s16, s10, 4
	s_lshl_b64 s[22:23], s[18:19], 6
	s_or_b32 s18, s10, 7
	s_add_i32 s10, s10, s78
	s_ashr_i32 s15, s14, 31
	s_ashr_i32 s17, s16, 31
	s_ashr_i32 s19, s18, 31
	s_ashr_i32 s11, s10, 31
	s_lshl_b64 s[14:15], s[14:15], 6
	s_lshl_b64 s[16:17], s[16:17], 6
	s_lshl_b64 s[18:19], s[18:19], 6
	s_lshl_b64 s[26:27], s[10:11], 6
	s_add_u32 s11, s26, s12
	s_addc_u32 s12, s27, s13
	v_or_b32_e32 v12, s11, v152
	v_mov_b32_e32 v13, s12
	v_lshlrev_b64 v[12:13], 5, v[12:13]
	v_lshl_add_u64 v[12:13], s[74:75], 0, v[12:13]
	v_lshl_add_u64 v[12:13], v[12:13], 0, s[4:5]
	s_mov_b64 s[4:5], 0x3000000
	v_lshl_add_u64 v[14:15], v[12:13], 0, s[4:5]
	s_mov_b32 s4, 0x3000000
	v_mad_i32_i24 v11, v9, s25, v11
	v_add_co_u32_e32 v12, vcc, s4, v12
	v_lshl_add_u64 v[8:9], v[10:11], 0, s[8:9]
	v_lshl_add_u64 v[10:11], v[10:11], 0, s[6:7]
	v_addc_co_u32_e32 v13, vcc, 0, v13, vcc
	v_lshl_add_u64 v[8:9], v[8:9], 0, v[6:7]
	v_lshl_add_u64 v[10:11], v[10:11], 0, v[0:1]
	global_load_dword v29, v[12:13], off
	s_nop 0
	global_load_dword v14, v[14:15], off offset:16
	s_nop 0
	global_load_dwordx4 v[64:67], v[8:9], off offset:1024
	global_load_dwordx2 v[102:103], v[10:11], off offset:512
	v_add_co_u32_e32 v8, vcc, s24, v8
	s_nop 1
	v_addc_co_u32_e32 v9, vcc, 0, v9, vcc
	v_add_co_u32_e32 v10, vcc, s24, v10
	s_nop 1
	v_addc_co_u32_e32 v11, vcc, 0, v11, vcc
	global_load_dwordx4 v[68:71], v[8:9], off offset:2048
	global_load_dwordx2 v[104:105], v[10:11], off offset:1536
	v_lshl_add_u64 v[8:9], v[4:5], 0, s[14:15]
	v_mad_u64_u32 v[10:11], s[4:5], v8, s25, v[2:3]
	v_mad_i32_i24 v11, v9, s25, v11
	v_lshl_add_u64 v[8:9], v[10:11], 0, s[8:9]
	v_lshl_add_u64 v[8:9], v[8:9], 0, v[6:7]
	v_lshl_add_u64 v[10:11], v[10:11], 0, s[6:7]
; __device__ __forceinline__ float fast_tanh(float x) { return 1.f - 2.f * __builtin_amdgcn_rcpf(1.f + __expf(2.f * x)); }
; __device__ __forceinline__ void mlstm_state_group(const Args& a, LAS unsigned char* lds, int bh, int grp, int tid, int wave, int lane) {
;     ...
;     for (int ci = 0; ci < ML_GROUP; ++ci) { const size_t r0 = rowbase + (size_t)(c0 + ci) * 64;
; #pragma unroll
;         for (int i = 0; i < 2; ++i) { rv[ci][i] = *(const u32x4*)(P + (r0 + 2 * lp + i) * NIN + PC_VM + h * 128 + pcg * 8); rk2[ci][i] = *(const u32x2*)(P + (r0 + 2 * lp + i) * NIN + PC_KM + h * 64 + pcg * 4); } }
;     {
;         const size_t r = rowbase + (size_t)(c0 + wave) * 64 + lane;
;         const float gi = GT[r * 8 + h], gf = GT[r * 8 + 4 + h];
;         const float ipre = 15.f * fast_tanh((gi + b_i) * (1.f / 15.f)), fpre = 15.f * fast_tanh((gf + b_f) * (1.f / 15.f));
;         float bc = -__logf(1.f + __expf(-fpre));
; #pragma unroll
;         for (int o = 1; o < 64; o <<= 1) { const float t = __shfl_up(bc, o); if (lane >= o) bc += t; }
	v_lshl_add_u64 v[10:11], v[10:11], 0, v[0:1]
	global_load_dwordx4 v[56:59], v[8:9], off offset:1024
	global_load_dwordx2 v[98:99], v[10:11], off offset:512
	v_add_co_u32_e32 v8, vcc, s24, v8
	s_nop 1
	v_addc_co_u32_e32 v9, vcc, 0, v9, vcc
	v_add_co_u32_e32 v10, vcc, s24, v10
	s_nop 1
	v_addc_co_u32_e32 v11, vcc, 0, v11, vcc
	global_load_dwordx4 v[60:63], v[8:9], off offset:2048
	global_load_dwordx2 v[100:101], v[10:11], off offset:1536
	v_lshl_add_u64 v[8:9], v[4:5], 0, s[16:17]
	v_mad_u64_u32 v[10:11], s[4:5], v8, s25, v[2:3]
	v_mad_i32_i24 v11, v9, s25, v11
	v_lshl_add_u64 v[8:9], v[10:11], 0, s[8:9]
	v_lshl_add_u64 v[8:9], v[8:9], 0, v[6:7]
	v_lshl_add_u64 v[10:11], v[10:11], 0, s[6:7]
	v_lshl_add_u64 v[10:11], v[10:11], 0, v[0:1]
	global_load_dwordx4 v[32:35], v[8:9], off offset:1024
	global_load_dwordx2 v[86:87], v[10:11], off offset:512
	v_add_co_u32_e32 v8, vcc, s24, v8
	s_nop 1
	v_addc_co_u32_e32 v9, vcc, 0, v9, vcc
	v_add_co_u32_e32 v10, vcc, s24, v10
	s_nop 1
	v_addc_co_u32_e32 v11, vcc, 0, v11, vcc
	global_load_dwordx4 v[36:39], v[8:9], off offset:2048
	global_load_dwordx2 v[88:89], v[10:11], off offset:1536
	v_lshl_add_u64 v[8:9], v[4:5], 0, s[20:21]
	v_mad_u64_u32 v[10:11], s[4:5], v8, s25, v[2:3]
	v_mad_i32_i24 v11, v9, s25, v11
	v_lshl_add_u64 v[8:9], v[10:11], 0, s[8:9]
	v_lshl_add_u64 v[8:9], v[8:9], 0, v[6:7]
	v_lshl_add_u64 v[10:11], v[10:11], 0, s[6:7]
	v_lshl_add_u64 v[10:11], v[10:11], 0, v[0:1]
	global_load_dwordx4 v[20:23], v[8:9], off offset:1024
	global_load_dwordx2 v[80:81], v[10:11], off offset:512
	v_add_co_u32_e32 v8, vcc, s24, v8
	s_nop 1
	v_addc_co_u32_e32 v9, vcc, 0, v9, vcc
	v_add_co_u32_e32 v10, vcc, s24, v10
	s_nop 1
	v_addc_co_u32_e32 v11, vcc, 0, v11, vcc
	global_load_dwordx4 v[24:27], v[8:9], off offset:2048
	global_load_dwordx2 v[82:83], v[10:11], off offset:1536
	v_lshl_add_u64 v[8:9], v[4:5], 0, s[22:23]
	v_mad_u64_u32 v[10:11], s[4:5], v8, s25, v[2:3]
	v_mad_i32_i24 v11, v9, s25, v11
	v_lshl_add_u64 v[8:9], v[10:11], 0, s[8:9]
	v_lshl_add_u64 v[12:13], v[8:9], 0, v[6:7]
	v_lshl_add_u64 v[8:9], v[10:11], 0, s[6:7]
	s_waitcnt vmcnt(16)
	v_add_f32_e32 v10, v16, v14
	v_mul_f32_e32 v10, 0x3d888889, v10
	v_add_f32_e32 v10, v10, v10
	v_mul_f32_e32 v10, 0x3fb8aa3b, v10
	v_exp_f32_e32 v16, v10
	v_lshl_add_u64 v[14:15], v[8:9], 0, v[0:1]
	global_load_dwordx4 v[8:11], v[12:13], off offset:1024
	global_load_dwordx2 v[74:75], v[14:15], off offset:512
	v_add_co_u32_e32 v12, vcc, s24, v12
	v_add_f32_e32 v16, 1.0, v16
	v_rcp_f32_e32 v16, v16
	v_addc_co_u32_e32 v13, vcc, 0, v13, vcc
	v_add_co_u32_e32 v14, vcc, s24, v14
	v_fma_f32 v16, v16, -2.0, 1.0
	v_mul_f32_e32 v16, 0xc1700000, v16
	v_mul_f32_e32 v16, 0x3fb8aa3b, v16
	v_exp_f32_e32 v16, v16
	v_addc_co_u32_e32 v15, vcc, 0, v15, vcc
	s_mov_b32 s4, 0x800000
	v_add_f32_e32 v16, 1.0, v16
	v_cmp_gt_f32_e32 vcc, s4, v16
	s_mov_b32 s4, 0x3f317217
	v_lshl_add_u64 v[4:5], v[4:5], 0, s[18:19]
	v_cndmask_b32_e64 v17, 0, 32, vcc
	v_ldexp_f32 v16, v16, v17
	v_log_f32_e32 v30, v16
	global_load_dwordx4 v[16:19], v[12:13], off offset:2048
	global_load_dwordx2 v[78:79], v[14:15], off offset:1536
	v_mbcnt_lo_u32_b32 v14, -1, 0
	v_mbcnt_hi_u32_b32 v72, -1, v14
	v_mul_f32_e32 v12, 0x3f317217, v30
	v_fma_f32 v12, v30, s4, -v12
	v_fmamk_f32 v12, v30, 0x3377d1cf, v12
	s_mov_b32 s4, 0x7f800000
	v_fmac_f32_e32 v12, 0x3f317217, v30
	v_cmp_lt_f32_e64 s[4:5], |v30|, s4
	v_mov_b32_e32 v13, 0x41b17218
	v_and_b32_e32 v73, 64, v72
	v_add_u32_e32 v14, -1, v72
	v_cndmask_b32_e64 v12, v30, v12, s[4:5]
	v_cndmask_b32_e32 v13, 0, v13, vcc
	v_cmp_lt_i32_e32 vcc, v14, v73
	v_sub_f32_e32 v12, v12, v13
	v_xor_b32_e32 v13, 0x80000000, v12
	v_cndmask_b32_e32 v14, v14, v72, vcc
	v_lshlrev_b32_e32 v14, 2, v14
	ds_bpermute_b32 v13, v14, v13
	v_mad_u64_u32 v[2:3], s[4:5], v4, s25, v[2:3]
	v_mad_i32_i24 v3, v5, s25, v3
	v_lshl_add_u64 v[4:5], v[2:3], 0, s[8:9]
	v_lshl_add_u64 v[4:5], v[4:5], 0, v[6:7]
	v_add_u32_e32 v7, -2, v72
	v_cmp_lt_i32_e64 s[4:5], v7, v73
	s_waitcnt lgkmcnt(0)
; __device__ __forceinline__ void mlstm_state_group(const Args& a, LAS unsigned char* lds, int bh, int grp, int tid, int wave, int lane) {
;     ...
;         float bc = -__logf(1.f + __expf(-fpre));
; #pragma unroll
;         for (int o = 1; o < 64; o <<= 1) { const float t = __shfl_up(bc, o); if (lane >= o) bc += t; }
;         const float bl = __shfl(bc, 63);
;         const float av = bl - bc + ipre;
;         float amax = av;
; #pragma unroll
;         for (int o = 1; o < 64; o <<= 1) amax = fmaxf(amax, __shfl_xor(amax, o));
;         T_av[wave * 64 + lane] = av;
;         if (lane == 0) { T_sc[wave] = bl; T_sc[8 + wave] = amax; CHS[(bh * 32 + c0 + wave) * 2] = bl; CHS[(bh * 32 + c0 + wave) * 2 + 1] = amax; }
	v_sub_f32_e32 v6, v13, v12
	v_cmp_eq_u32_e32 vcc, 0, v152
	v_cndmask_b32_e64 v7, v7, v72, s[4:5]
	v_lshlrev_b32_e32 v7, 2, v7
	v_cndmask_b32_e64 v6, v6, -v12, vcc
	ds_bpermute_b32 v7, v7, v6
	v_lshl_add_u64 v[2:3], v[2:3], 0, s[6:7]
	v_lshl_add_u64 v[0:1], v[2:3], 0, v[0:1]
	v_cmp_gt_u32_e64 s[4:5], 2, v152
	global_load_dwordx4 v[12:15], v[4:5], off offset:1024
	global_load_dwordx2 v[76:77], v[0:1], off offset:512
	s_waitcnt lgkmcnt(0)
	v_add_f32_e32 v2, v6, v7
	v_cndmask_b32_e64 v6, v2, v6, s[4:5]
	v_add_u32_e32 v2, -4, v72
	v_cmp_lt_i32_e64 s[4:5], v2, v73
	s_nop 1
	v_cndmask_b32_e64 v2, v2, v72, s[4:5]
	v_lshlrev_b32_e32 v2, 2, v2
	ds_bpermute_b32 v7, v2, v6
	v_add_co_u32_e64 v2, s[4:5], s24, v4
	s_waitcnt lgkmcnt(0)
	v_add_f32_e32 v4, v6, v7
	v_addc_co_u32_e64 v3, s[4:5], 0, v5, s[4:5]
	v_cmp_gt_u32_e64 s[4:5], 4, v152
	v_add_u32_e32 v5, -8, v72
	s_nop 0
	v_cndmask_b32_e64 v4, v4, v6, s[4:5]
	v_cmp_lt_i32_e64 s[4:5], v5, v73
	v_add_f32_e32 v6, v28, v29
	v_mul_f32_e32 v6, 0x3d888889, v6
	v_cndmask_b32_e64 v5, v5, v72, s[4:5]
	v_lshlrev_b32_e32 v5, 2, v5
	ds_bpermute_b32 v5, v5, v4
	v_add_co_u32_e64 v0, s[4:5], s24, v0
	v_add_f32_e32 v6, v6, v6
	s_nop 0
	v_addc_co_u32_e64 v1, s[4:5], 0, v1, s[4:5]
	s_waitcnt lgkmcnt(0)
	v_add_f32_e32 v5, v4, v5
	v_cmp_gt_u32_e64 s[4:5], 8, v152
	global_load_dwordx4 v[28:31], v[2:3], off offset:2048
	global_load_dwordx2 v[84:85], v[0:1], off offset:1536
	v_cndmask_b32_e64 v4, v5, v4, s[4:5]
	v_add_u32_e32 v5, -16, v72
	v_cmp_lt_i32_e64 s[4:5], v5, v73
	v_mul_f32_e32 v6, 0x3fb8aa3b, v6
	v_exp_f32_e32 v6, v6
	v_cndmask_b32_e64 v5, v5, v72, s[4:5]
	v_lshlrev_b32_e32 v5, 2, v5
	ds_bpermute_b32 v5, v5, v4
	v_cmp_gt_u32_e64 s[4:5], 16, v152
	v_add_f32_e32 v0, 1.0, v6
	v_rcp_f32_e32 v1, v0
	s_waitcnt lgkmcnt(0)
	v_add_f32_e32 v5, v4, v5
	v_cndmask_b32_e64 v4, v5, v4, s[4:5]
	v_subrev_u32_e32 v5, 32, v72
	v_cmp_lt_i32_e64 s[4:5], v5, v73
	v_fma_f32 v1, v1, -2.0, 1.0
	s_nop 0
	v_cndmask_b32_e64 v5, v5, v72, s[4:5]
	v_lshlrev_b32_e32 v5, 2, v5
	ds_bpermute_b32 v5, v5, v4
	v_cmp_gt_u32_e64 s[4:5], 32, v152
	s_waitcnt lgkmcnt(0)
	v_add_f32_e32 v0, v4, v5
	v_cndmask_b32_e64 v2, v0, v4, s[4:5]
	v_bfrev_b32_e32 v0, 0.5
	v_lshl_or_b32 v0, v72, 2, v0
	ds_bpermute_b32 v0, v0, v2
	v_xor_b32_e32 v4, 2, v72
	s_waitcnt lgkmcnt(0)
	v_sub_f32_e32 v2, v0, v2
	v_fmamk_f32 v3, v1, 0x41700000, v2
	v_add_u32_e32 v2, 64, v73
	v_xor_b32_e32 v1, 1, v72
	v_cmp_lt_i32_e64 s[4:5], v1, v2
	s_nop 1
	v_cndmask_b32_e64 v1, v72, v1, s[4:5]
	v_lshlrev_b32_e32 v107, 2, v1
	ds_bpermute_b32 v1, v107, v3
	v_cmp_lt_i32_e64 s[4:5], v4, v2
	s_waitcnt lgkmcnt(0)
	v_max_f32_e32 v1, v1, v1
	v_cndmask_b32_e64 v4, v72, v4, s[4:5]
	v_max_f32_e32 v1, v3, v1
	v_lshlrev_b32_e32 v106, 2, v4
	ds_bpermute_b32 v4, v106, v1
	s_waitcnt lgkmcnt(0)
	v_max_f32_e32 v4, v4, v4
	v_max_f32_e32 v1, v1, v4
	v_xor_b32_e32 v4, 4, v72
	v_cmp_lt_i32_e64 s[4:5], v4, v2
	s_nop 1
	v_cndmask_b32_e64 v4, v72, v4, s[4:5]
	v_lshlrev_b32_e32 v73, 2, v4
	ds_bpermute_b32 v4, v73, v1
	s_waitcnt lgkmcnt(0)
	v_max_f32_e32 v4, v4, v4
	v_max_f32_e32 v1, v1, v4
	v_xor_b32_e32 v4, 8, v72
	v_cmp_lt_i32_e64 s[4:5], v4, v2
	s_nop 1
	v_cndmask_b32_e64 v4, v72, v4, s[4:5]
	v_lshlrev_b32_e32 v4, 2, v4
	ds_bpermute_b32 v4, v4, v1
	s_waitcnt lgkmcnt(0)
	v_max_f32_e32 v4, v4, v4
	v_max_f32_e32 v1, v1, v4
	v_xor_b32_e32 v4, 16, v72
	v_cmp_lt_i32_e64 s[4:5], v4, v2
	s_nop 1
	v_cndmask_b32_e64 v4, v72, v4, s[4:5]
	v_lshlrev_b32_e32 v4, 2, v4
	ds_bpermute_b32 v4, v4, v1
	s_waitcnt lgkmcnt(0)
	v_max_f32_e32 v4, v4, v4
	v_max_f32_e32 v1, v1, v4
	v_xor_b32_e32 v4, 32, v72
	v_cmp_lt_i32_e64 s[4:5], v4, v2
	s_nop 1
	v_cndmask_b32_e64 v2, v72, v4, s[4:5]
	v_lshlrev_b32_e32 v2, 2, v2
	ds_bpermute_b32 v2, v2, v1
	s_lshl_b32 s4, s78, 8
	s_add_i32 s4, s4, 0
	v_lshl_add_u32 v4, v152, 2, s4
	v_add_u32_e32 v4, 0x1aa00, v4
	ds_write_b32 v4, v3
	s_and_saveexec_b64 s[4:5], vcc
	s_cbranch_execz .LBB0_1081
	s_lshl_b32 s6, s0, 6
	s_lshl_b32 s7, s10, 1
	s_add_i32 s6, s7, s6
	s_ashr_i32 s7, s6, 31
	s_lshl_b64 s[6:7], s[6:7], 2
	s_add_u32 s6, s74, s6
	s_addc_u32 s7, s75, s7
	s_lshl_b32 s8, s78, 2
	s_add_i32 s8, s8, 0
	s_waitcnt lgkmcnt(1)
	v_max_f32_e32 v2, v2, v2
	v_max_f32_e32 v1, v1, v1
	s_add_i32 s8, s8, 0x1ca00
	v_max_f32_e32 v1, v1, v2
	v_mov_b32_e32 v2, s8
	ds_write2_b32 v2, v0, v1 offset1:8
	v_mov_b32_e32 v2, 0x1e010000
	global_store_dwordx2 v2, v[0:1], s[6:7] offset:2048
